# attention: K / V fragment base adds also moved before the step barrier (the body's first instructions behind the barrier are the LDS reads)
# speedup vs baseline: 1.0062x; 1.0038x over previous
; #define LAS __attribute__((address_space(3)))
; __device__ __forceinline__ void attn_phase(LAS unsigned char* lds, const bf16_t* __restrict__ Q, const bf16_t* __restrict__ KN, const bf16_t* __restrict__ KR,
;                                            const bf16_t* __restrict__ VT, bf16_t* AO, int vcu, int G, int tid, int lane, int wave) {
;     ...
;                 const LAS unsigned char* kA = buf + (pr * KP + 8 * hi) * 2; const LAS unsigned char* vA = buf + KBUF + (r32 * VP + 8 * hi) * 2;
.Lat_both:
	v_add_u32_e32 v1, s37, v222
	v_add_u32_e32 v225, s37, v223
	s_branch .Lat_both_c

; __device__ __forceinline__ void attn_phase(LAS unsigned char* lds, const bf16_t* __restrict__ Q, const bf16_t* __restrict__ KN, const bf16_t* __restrict__ KR,
;                                            const bf16_t* __restrict__ VT, bf16_t* AO, int vcu, int G, int tid, int lane, int wave) {
;     ...
;                 if (2 * t + 1 <= qc) {
;                     bf16x8 kf[12], kf2[12], vf[8], vf2[8], pa[4], pb2[4]; f32x16 a0, a1, b0, b1;
;                     attn_ldk(kf, kA);
;                     __builtin_amdgcn_sched_barrier(0);
;                     attn_qk(a0, a1, kf, qf);
;                     attn_ldk(kf2, kA + 64 * KP * 2);
;                     __builtin_amdgcn_sched_barrier(0);
;                     attn_qk(b0, b1, kf2, qf);
;                     attn_softmax(a0, a1, pa, o0, o1, m_run, l_run);
;                     attn_ldv(vf, vA);
;                     __builtin_amdgcn_sched_barrier(0);
;                     PREFETCH_NEXT();
;                     attn_ldv(vf2, vA + 128);
;                     __builtin_amdgcn_sched_barrier(0);
;                     attn_pv(vf, pa, o0, o1);
;                     attn_softmax(b0, b1, pb2, o0, o1, m_run, l_run);
;                     __builtin_amdgcn_sched_barrier(0);
;                     attn_pv(vf2, pb2, o0, o1);
.Lat_both_c:
	ds_read_b128 v[138:141], v1
	ds_read_b128 v[142:145], v1 offset:32
	ds_read_b128 v[146:149], v1 offset:64
	ds_read_b128 v[150:153], v1 offset:96
	ds_read_b128 v[154:157], v1 offset:128
	ds_read_b128 v[158:161], v1 offset:160
	ds_read_b128 v[162:165], v1 offset:6656
	ds_read_b128 v[166:169], v1 offset:6688
	s_waitcnt vmcnt(5)
	s_waitcnt lgkmcnt(7)
	v_mfma_f32_32x32x16_bf16 v[34:49], v[138:141], v[114:117], v[98:113]
	ds_read_b128 v[138:141], v1 offset:6720
	s_waitcnt lgkmcnt(7)
	v_mfma_f32_32x32x16_bf16 v[34:49], v[142:145], v[118:121], v[34:49]
	ds_read_b128 v[142:145], v1 offset:6752
	s_waitcnt lgkmcnt(7)
	v_mfma_f32_32x32x16_bf16 v[34:49], v[146:149], v[122:125], v[34:49]
	ds_read_b128 v[146:149], v1 offset:6784
	s_waitcnt lgkmcnt(7)
	v_mfma_f32_32x32x16_bf16 v[34:49], v[150:153], v[126:129], v[34:49]
	ds_read_b128 v[150:153], v1 offset:6816
	s_waitcnt lgkmcnt(7)
	v_mfma_f32_32x32x16_bf16 v[34:49], v[154:157], v[130:133], v[34:49]
	ds_read_b128 v[154:157], v1 offset:13312
	s_waitcnt lgkmcnt(7)
	v_mfma_f32_32x32x16_bf16 v[34:49], v[158:161], v[134:137], v[34:49]
	ds_read_b128 v[158:161], v1 offset:19968
	s_cmp_lg_u32 s7, 0
	s_cbranch_scc1 .Lat_plain_A2
	s_waitcnt lgkmcnt(7)
	v_mfma_f32_32x32x16_bf16 v[50:65], v[162:165], v[114:117], v[98:113]
	ds_read_b128 v[162:165], v1 offset:13344
	s_waitcnt lgkmcnt(7)
	v_mfma_f32_32x32x16_bf16 v[50:65], v[166:169], v[118:121], v[50:65]
	ds_read_b128 v[166:169], v1 offset:20000
	s_nop 2
	v_exp_f32_e32 v34, v34
	v_exp_f32_e32 v35, v35
	v_exp_f32_e32 v36, v36
	v_exp_f32_e32 v37, v37
	s_waitcnt lgkmcnt(7)
	v_mfma_f32_32x32x16_bf16 v[50:65], v[138:141], v[122:125], v[50:65]
	ds_read_b128 v[138:141], v1 offset:13376
	v_exp_f32_e32 v38, v38
	v_exp_f32_e32 v39, v39
	v_exp_f32_e32 v40, v40
	s_waitcnt lgkmcnt(7)
	v_mfma_f32_32x32x16_bf16 v[50:65], v[142:145], v[126:129], v[50:65]
	ds_read_b128 v[142:145], v1 offset:20032
	v_exp_f32_e32 v41, v41
	v_exp_f32_e32 v42, v42
	v_exp_f32_e32 v43, v43
	s_waitcnt lgkmcnt(7)
	v_mfma_f32_32x32x16_bf16 v[50:65], v[146:149], v[130:133], v[50:65]
	ds_read_b128 v[146:149], v1 offset:13408
	v_exp_f32_e32 v44, v44
	v_exp_f32_e32 v45, v45
	v_exp_f32_e32 v46, v46
	s_waitcnt lgkmcnt(7)
	v_mfma_f32_32x32x16_bf16 v[50:65], v[150:153], v[134:137], v[50:65]
	ds_read_b128 v[150:153], v1 offset:20064
	v_exp_f32_e32 v47, v47
	v_exp_f32_e32 v48, v48
	v_exp_f32_e32 v49, v49
	s_waitcnt lgkmcnt(7)
	v_mfma_f32_32x32x16_bf16 v[66:81], v[154:157], v[114:117], v[98:113]
	ds_read_b128 v[154:157], v1 offset:13440
	s_waitcnt lgkmcnt(7)
	v_mfma_f32_32x32x16_bf16 v[82:97], v[158:161], v[114:117], v[98:113]
	ds_read_b128 v[158:161], v1 offset:20096
	s_nop 1
	v_exp_f32_e32 v50, v50
	v_exp_f32_e32 v51, v51
	v_exp_f32_e32 v52, v52
	v_exp_f32_e32 v53, v53
	s_waitcnt lgkmcnt(7)
	v_mfma_f32_32x32x16_bf16 v[66:81], v[162:165], v[118:121], v[66:81]
	ds_read_b128 v[162:165], v1 offset:13472
	v_exp_f32_e32 v54, v54
	v_exp_f32_e32 v55, v55
	v_exp_f32_e32 v56, v56
	s_waitcnt lgkmcnt(7)
	v_mfma_f32_32x32x16_bf16 v[82:97], v[166:169], v[118:121], v[82:97]
	ds_read_b128 v[166:169], v1 offset:20128
	v_exp_f32_e32 v57, v57
	v_exp_f32_e32 v58, v58
	v_exp_f32_e32 v59, v59
	s_waitcnt lgkmcnt(7)
	v_mfma_f32_32x32x16_bf16 v[66:81], v[138:141], v[122:125], v[66:81]
	ds_read_b128 v[170:173], v225 offset:26624
	v_exp_f32_e32 v60, v60
	v_exp_f32_e32 v61, v61
	v_exp_f32_e32 v62, v62
	s_waitcnt lgkmcnt(7)
	v_mfma_f32_32x32x16_bf16 v[82:97], v[142:145], v[122:125], v[82:97]
	ds_read_b128 v[174:177], v225 offset:35328
	v_exp_f32_e32 v63, v63
	v_exp_f32_e32 v64, v64
	v_exp_f32_e32 v65, v65
	s_waitcnt lgkmcnt(7)
	v_mfma_f32_32x32x16_bf16 v[66:81], v[146:149], v[126:129], v[66:81]
	ds_read_b128 v[178:181], v225 offset:26656
	v_add_f32_e32 v250, v34, v36
	v_add_f32_e32 v251, v35, v37
	v_add_f32_e32 v252, v50, v52
	v_add_f32_e32 v253, v51, v53
	v_add_f32_e32 v250, v250, v38
	v_add_f32_e32 v251, v251, v39
	s_waitcnt lgkmcnt(7)
	v_mfma_f32_32x32x16_bf16 v[82:97], v[150:153], v[126:129], v[82:97]
	ds_read_b128 v[182:185], v225 offset:35360
	v_add_f32_e32 v252, v252, v54
	v_add_f32_e32 v253, v253, v55
	v_add_f32_e32 v250, v250, v40
	v_add_f32_e32 v251, v251, v41
	v_add_f32_e32 v252, v252, v56
	s_waitcnt lgkmcnt(7)
	v_mfma_f32_32x32x16_bf16 v[66:81], v[154:157], v[130:133], v[66:81]
	ds_read_b128 v[186:189], v225 offset:26688
	v_add_f32_e32 v253, v253, v57
	v_add_f32_e32 v250, v250, v42
	v_add_f32_e32 v251, v251, v43
	v_add_f32_e32 v252, v252, v58
	v_add_f32_e32 v253, v253, v59
	s_waitcnt lgkmcnt(7)
	v_mfma_f32_32x32x16_bf16 v[82:97], v[158:161], v[130:133], v[82:97]
	ds_read_b128 v[190:193], v225 offset:35392
	v_add_f32_e32 v250, v250, v44
	v_add_f32_e32 v251, v251, v45
	v_add_f32_e32 v252, v252, v60
	v_add_f32_e32 v253, v253, v61
	v_add_f32_e32 v250, v250, v46
	s_waitcnt lgkmcnt(7)
	v_mfma_f32_32x32x16_bf16 v[66:81], v[162:165], v[134:137], v[66:81]
	v_add_f32_e32 v251, v251, v47
	v_add_f32_e32 v252, v252, v62
	v_add_f32_e32 v253, v253, v63
	v_add_f32_e32 v250, v250, v48
	v_add_f32_e32 v251, v251, v49
	s_waitcnt lgkmcnt(6)
	v_mfma_f32_32x32x16_bf16 v[82:97], v[166:169], v[134:137], v[82:97]
	v_add_f32_e32 v252, v252, v64
	v_add_f32_e32 v253, v253, v65
	v_add_f32_e32 v250, v250, v252
	v_add_f32_e32 v251, v251, v253
	v_add_f32_e32 v1, v250, v251
	s_mov_b32 s41, 0
	s_branch .Lat_sum_A2

; __device__ __forceinline__ void attn_phase(LAS unsigned char* lds, const bf16_t* __restrict__ Q, const bf16_t* __restrict__ KN, const bf16_t* __restrict__ KR,
;                                            const bf16_t* __restrict__ VT, bf16_t* AO, int vcu, int G, int tid, int lane, int wave) {
;     ...
;                 } else if (2 * t <= qc) {
;                     bf16x8 kf[12], vf[8], pa[4]; f32x16 a0, a1;
;                     PREFETCH_NEXT();
;                     attn_ldk(kf, kA);
;                     __builtin_amdgcn_sched_barrier(0);
;                     attn_qk(a0, a1, kf, qf);
;                     __builtin_amdgcn_sched_barrier(0);
;                     attn_ldv(vf, vA);
;                     __builtin_amdgcn_sched_barrier(0);
;                     attn_softmax(a0, a1, pa, o0, o1, m_run, l_run);
;                     __builtin_amdgcn_sched_barrier(0);
;                     attn_pv(vf, pa, o0, o1);
.Lat_single_c:
	ds_read_b128 v[138:141], v1
	ds_read_b128 v[142:145], v1 offset:6656
	ds_read_b128 v[146:149], v1 offset:32
	ds_read_b128 v[150:153], v1 offset:6688
	ds_read_b128 v[154:157], v1 offset:64
	ds_read_b128 v[158:161], v1 offset:6720
	ds_read_b128 v[162:165], v1 offset:96
	ds_read_b128 v[166:169], v1 offset:6752
	s_waitcnt vmcnt(5)
	s_waitcnt lgkmcnt(7)
	v_mfma_f32_32x32x16_bf16 v[34:49], v[138:141], v[114:117], v[98:113]
	ds_read_b128 v[138:141], v1 offset:128
	s_waitcnt lgkmcnt(7)
	v_mfma_f32_32x32x16_bf16 v[50:65], v[142:145], v[114:117], v[98:113]
	ds_read_b128 v[142:145], v1 offset:6784
	s_waitcnt lgkmcnt(7)
	v_mfma_f32_32x32x16_bf16 v[34:49], v[146:149], v[118:121], v[34:49]
	ds_read_b128 v[146:149], v1 offset:160
	s_waitcnt lgkmcnt(7)
	v_mfma_f32_32x32x16_bf16 v[50:65], v[150:153], v[118:121], v[50:65]
	ds_read_b128 v[150:153], v1 offset:6816
	s_waitcnt lgkmcnt(7)
	v_mfma_f32_32x32x16_bf16 v[34:49], v[154:157], v[122:125], v[34:49]
	ds_read_b128 v[170:173], v225 offset:26624
	s_waitcnt lgkmcnt(7)
	v_mfma_f32_32x32x16_bf16 v[50:65], v[158:161], v[122:125], v[50:65]
	ds_read_b128 v[174:177], v225 offset:35328
	s_waitcnt lgkmcnt(7)
	v_mfma_f32_32x32x16_bf16 v[34:49], v[162:165], v[126:129], v[34:49]
	ds_read_b128 v[178:181], v225 offset:26656
	s_waitcnt lgkmcnt(7)
	v_mfma_f32_32x32x16_bf16 v[50:65], v[166:169], v[126:129], v[50:65]
	ds_read_b128 v[182:185], v225 offset:35360
	s_waitcnt lgkmcnt(7)
	v_mfma_f32_32x32x16_bf16 v[34:49], v[138:141], v[130:133], v[34:49]
	ds_read_b128 v[186:189], v225 offset:26688
	s_waitcnt lgkmcnt(7)
	v_mfma_f32_32x32x16_bf16 v[50:65], v[142:145], v[130:133], v[50:65]
	ds_read_b128 v[190:193], v225 offset:35392
	s_waitcnt lgkmcnt(7)
	v_mfma_f32_32x32x16_bf16 v[34:49], v[146:149], v[134:137], v[34:49]
	s_waitcnt lgkmcnt(6)
	v_mfma_f32_32x32x16_bf16 v[50:65], v[150:153], v[134:137], v[50:65]
	s_mov_b32 s41, 0
	s_cmp_lg_u32 s7, 0
	s_cbranch_scc1 .Lat_first_A1

; #define LAS __attribute__((address_space(3)))
; __device__ __forceinline__ void attn_phase(LAS unsigned char* lds, const bf16_t* __restrict__ Q, const bf16_t* __restrict__ KN, const bf16_t* __restrict__ KR,
;                                            const bf16_t* __restrict__ VT, bf16_t* AO, int vcu, int G, int tid, int lane, int wave) {
;     ...
;                 const LAS unsigned char* kA = buf + (pr * KP + 8 * hi) * 2; const LAS unsigned char* vA = buf + KBUF + (r32 * VP + 8 * hi) * 2;
;                 if (2 * t + 1 <= qc) {
;                     bf16x8 kf[12], kf2[12], vf[8], vf2[8], pa[4], pb2[4]; f32x16 a0, a1, b0, b1;
;                     attn_ldk(kf, kA);
;                     __builtin_amdgcn_sched_barrier(0);
;                     attn_qk(a0, a1, kf, qf);
;                     attn_ldk(kf2, kA + 64 * KP * 2);
;                     __builtin_amdgcn_sched_barrier(0);
;                     attn_qk(b0, b1, kf2, qf);
;                     attn_softmax(a0, a1, pa, o0, o1, m_run, l_run);
;                     attn_ldv(vf, vA);
;                     __builtin_amdgcn_sched_barrier(0);
;                     PREFETCH_NEXT();
;                     attn_ldv(vf2, vA + 128);
;                     __builtin_amdgcn_sched_barrier(0);
;                     attn_pv(vf, pa, o0, o1);
;                     attn_softmax(b0, b1, pb2, o0, o1, m_run, l_run);
;                     __builtin_amdgcn_sched_barrier(0);
;                     attn_pv(vf2, pb2, o0, o1);
;                 } else if (2 * t <= qc) {
.Lat_rot_nopf:
	v_add_u32_e32 v1, s37, v222
	v_add_u32_e32 v225, s37, v223
	s_lshl_b32 s40, s8, 1
	s_cmp_lt_u32 s40, s33
	s_cbranch_scc1 .Lat_both_b
	s_cmp_eq_u32 s40, s33
	s_cbranch_scc1 .Lat_single_b
	s_barrier
	s_branch .Lat_tail
